# P3 K-loop LDS-DMA staging loads (Y and W_out tiles) with nt policy, on top of x loads nt
# baseline (speedup 1.0000x reference)
.LBB0_382:
	ds_read_b128 v[140:143], v146
	ds_read_b128 v[150:153], v146 offset:1024
	ds_read_b128 v[154:157], v146 offset:2048
	ds_read_b128 v[158:161], v146 offset:3072
	ds_read_b128 v[162:165], v147
	ds_read_b128 v[166:169], v147 offset:1024
	ds_read_b128 v[170:173], v147 offset:2048
	ds_read_b128 v[174:177], v147 offset:3072
	s_add_u32 s8, s46, 0xfffc0080
	s_addc_u32 s9, s47, -1
	s_cmp_eq_u32 s72, 12
	s_cselect_b32 s51, s37, s9
	s_cselect_b32 s50, s45, s8
	s_cselect_b32 s49, s29, s71
	s_cselect_b32 s48, s69, s70
	v_lshl_add_u64 v[190:191], s[46:47], 0, v[132:133]
	s_add_i32 m0, s57, 0xc000
	ds_read_b128 v[178:181], v148
	ds_read_b128 v[182:185], v148 offset:1024
	ds_read_b128 v[186:189], v148 offset:2048
	ds_read_b128 v[196:199], v148 offset:3072
	ds_read_b128 v[200:203], v148 offset:4096
	ds_read_b128 v[204:207], v148 offset:5120
	ds_read_b128 v[208:211], v148 offset:6144
	ds_read_b128 v[212:215], v148 offset:7168
	global_load_lds_dwordx4 v[190:191], off nt
	v_lshl_add_u64 v[190:191], s[46:47], 0, v[134:135]
	s_add_i32 m0, s57, 0xe000
	s_nop 0
	global_load_lds_dwordx4 v[190:191], off nt
	s_waitcnt vmcnt(8)
	s_waitcnt lgkmcnt(0)
	s_barrier
	s_setprio 1
	s_waitcnt lgkmcnt(0)
	v_mfma_f32_16x16x32_bf16 v[124:127], v[140:143], v[178:181], v[124:127]
	v_mfma_f32_16x16x32_bf16 v[120:123], v[154:157], v[178:181], v[120:123]
	v_mfma_f32_16x16x32_bf16 v[108:111], v[140:143], v[186:189], v[108:111]
	v_mfma_f32_16x16x32_bf16 v[104:107], v[154:157], v[186:189], v[104:107]
	v_mfma_f32_16x16x32_bf16 v[92:95], v[140:143], v[200:203], v[92:95]
	v_mfma_f32_16x16x32_bf16 v[88:91], v[154:157], v[200:203], v[88:91]
	v_mfma_f32_16x16x32_bf16 v[76:79], v[140:143], v[208:211], v[76:79]
	v_mfma_f32_16x16x32_bf16 v[72:75], v[154:157], v[208:211], v[72:75]
	v_mfma_f32_16x16x32_bf16 v[124:127], v[150:153], v[182:185], v[124:127]
	v_mfma_f32_16x16x32_bf16 v[120:123], v[158:161], v[182:185], v[120:123]
	v_mfma_f32_16x16x32_bf16 v[108:111], v[150:153], v[196:199], v[108:111]
	v_mfma_f32_16x16x32_bf16 v[104:107], v[158:161], v[196:199], v[104:107]
	v_mfma_f32_16x16x32_bf16 v[92:95], v[150:153], v[204:207], v[92:95]
	v_mfma_f32_16x16x32_bf16 v[88:91], v[158:161], v[204:207], v[88:91]
	v_mfma_f32_16x16x32_bf16 v[76:79], v[150:153], v[212:215], v[76:79]
	v_mfma_f32_16x16x32_bf16 v[72:75], v[158:161], v[212:215], v[72:75]
	s_setprio 0
	s_setprio 1
	v_mfma_f32_16x16x32_bf16 v[116:119], v[162:165], v[178:181], v[116:119]
	v_mfma_f32_16x16x32_bf16 v[112:115], v[170:173], v[178:181], v[112:115]
	v_mfma_f32_16x16x32_bf16 v[100:103], v[162:165], v[186:189], v[100:103]
	v_mfma_f32_16x16x32_bf16 v[96:99], v[170:173], v[186:189], v[96:99]
	v_mfma_f32_16x16x32_bf16 v[84:87], v[162:165], v[200:203], v[84:87]
	v_mfma_f32_16x16x32_bf16 v[80:83], v[170:173], v[200:203], v[80:83]
	v_mfma_f32_16x16x32_bf16 v[68:71], v[162:165], v[208:211], v[68:71]
	v_mfma_f32_16x16x32_bf16 v[64:67], v[170:173], v[208:211], v[64:67]
	v_mfma_f32_16x16x32_bf16 v[116:119], v[166:169], v[182:185], v[116:119]
	v_mfma_f32_16x16x32_bf16 v[112:115], v[174:177], v[182:185], v[112:115]
	v_mfma_f32_16x16x32_bf16 v[100:103], v[166:169], v[196:199], v[100:103]
	v_mfma_f32_16x16x32_bf16 v[96:99], v[174:177], v[196:199], v[96:99]
	v_mfma_f32_16x16x32_bf16 v[84:87], v[166:169], v[204:207], v[84:87]
	v_mfma_f32_16x16x32_bf16 v[80:83], v[174:177], v[204:207], v[80:83]
	v_mfma_f32_16x16x32_bf16 v[68:71], v[166:169], v[212:215], v[68:71]
	v_mfma_f32_16x16x32_bf16 v[64:67], v[174:177], v[212:215], v[64:67]
	s_setprio 0
	s_barrier
	s_add_i32 s8, s66, s56
	v_lshl_add_u64 v[190:191], s[48:49], 0, v[128:129]
	s_mov_b32 m0, s8
	ds_read_b128 v[178:181], v148 offset:16384
	ds_read_b128 v[182:185], v148 offset:17408
	ds_read_b128 v[186:189], v148 offset:18432
	ds_read_b128 v[196:199], v148 offset:19456
	ds_read_b128 v[200:203], v148 offset:20480
	ds_read_b128 v[204:207], v148 offset:21504
	ds_read_b128 v[208:211], v148 offset:22528
	ds_read_b128 v[212:215], v148 offset:23552
	global_load_lds_dwordx4 v[190:191], off nt
	s_add_i32 m0, s8, 0x2000
	s_add_u32 s74, s48, 0x40000
	v_lshl_add_u64 v[216:217], s[48:49], 0, v[130:131]
	s_addc_u32 s75, s49, 0
	s_add_i32 s8, s67, s56
	global_load_lds_dwordx4 v[216:217], off nt
	v_lshl_add_u64 v[218:219], s[74:75], 0, v[128:129]
	s_mov_b32 m0, s8
	v_lshl_add_u64 v[220:221], s[50:51], 0, v[130:131]
	global_load_lds_dwordx4 v[218:219], off nt
	v_lshl_add_u64 v[218:219], s[74:75], 0, v[130:131]
	s_add_i32 m0, s8, 0x2000
	s_nop 0
	global_load_lds_dwordx4 v[218:219], off nt
	v_lshl_add_u64 v[218:219], s[50:51], 0, v[128:129]
	s_mov_b32 m0, s57
	s_nop 0
	global_load_lds_dwordx4 v[218:219], off nt
	s_mov_b32 m0, s58
	s_nop 0
	global_load_lds_dwordx4 v[220:221], off nt
	s_waitcnt vmcnt(8)
	s_waitcnt lgkmcnt(0)
	s_barrier
	s_setprio 1
	s_waitcnt lgkmcnt(0)
	v_mfma_f32_16x16x32_bf16 v[60:63], v[140:143], v[178:181], v[60:63]
	v_mfma_f32_16x16x32_bf16 v[56:59], v[154:157], v[178:181], v[56:59]
	v_mfma_f32_16x16x32_bf16 v[44:47], v[140:143], v[186:189], v[44:47]
	v_mfma_f32_16x16x32_bf16 v[40:43], v[154:157], v[186:189], v[40:43]
	v_mfma_f32_16x16x32_bf16 v[28:31], v[140:143], v[200:203], v[28:31]
	v_mfma_f32_16x16x32_bf16 v[24:27], v[154:157], v[200:203], v[24:27]
	v_mfma_f32_16x16x32_bf16 v[12:15], v[140:143], v[208:211], v[12:15]
	v_mfma_f32_16x16x32_bf16 v[8:11], v[154:157], v[208:211], v[8:11]
	v_mfma_f32_16x16x32_bf16 v[60:63], v[150:153], v[182:185], v[60:63]
	v_mfma_f32_16x16x32_bf16 v[56:59], v[158:161], v[182:185], v[56:59]
	v_mfma_f32_16x16x32_bf16 v[44:47], v[150:153], v[196:199], v[44:47]
	v_mfma_f32_16x16x32_bf16 v[40:43], v[158:161], v[196:199], v[40:43]
	v_mfma_f32_16x16x32_bf16 v[28:31], v[150:153], v[204:207], v[28:31]
	v_mfma_f32_16x16x32_bf16 v[24:27], v[158:161], v[204:207], v[24:27]
	v_mfma_f32_16x16x32_bf16 v[12:15], v[150:153], v[212:215], v[12:15]
	v_mfma_f32_16x16x32_bf16 v[8:11], v[158:161], v[212:215], v[8:11]
	s_setprio 0
	s_setprio 1
	v_mfma_f32_16x16x32_bf16 v[52:55], v[162:165], v[178:181], v[52:55]
	v_mfma_f32_16x16x32_bf16 v[48:51], v[170:173], v[178:181], v[48:51]
	v_mfma_f32_16x16x32_bf16 v[36:39], v[162:165], v[186:189], v[36:39]
	v_mfma_f32_16x16x32_bf16 v[32:35], v[170:173], v[186:189], v[32:35]
	v_mfma_f32_16x16x32_bf16 v[20:23], v[162:165], v[200:203], v[20:23]
	v_mfma_f32_16x16x32_bf16 v[16:19], v[170:173], v[200:203], v[16:19]
	v_mfma_f32_16x16x32_bf16 v[4:7], v[162:165], v[208:211], v[4:7]
	v_mfma_f32_16x16x32_bf16 v[0:3], v[170:173], v[208:211], v[0:3]
	v_mfma_f32_16x16x32_bf16 v[52:55], v[166:169], v[182:185], v[52:55]
	v_mfma_f32_16x16x32_bf16 v[48:51], v[174:177], v[182:185], v[48:51]
	v_mfma_f32_16x16x32_bf16 v[36:39], v[166:169], v[196:199], v[36:39]
	v_mfma_f32_16x16x32_bf16 v[32:35], v[174:177], v[196:199], v[32:35]
	v_mfma_f32_16x16x32_bf16 v[20:23], v[166:169], v[204:207], v[20:23]
	v_mfma_f32_16x16x32_bf16 v[16:19], v[174:177], v[204:207], v[16:19]
	v_mfma_f32_16x16x32_bf16 v[4:7], v[166:169], v[212:215], v[4:7]
	v_mfma_f32_16x16x32_bf16 v[0:3], v[174:177], v[212:215], v[0:3]
	s_setprio 0
	s_barrier
	s_add_i32 s8, 0, 0x18000
	v_add_u32_e32 v149, s8, v145
	s_add_i32 s9, 0, 0x1c000
	ds_read_b128 v[140:143], v149
	ds_read_b128 v[150:153], v149 offset:1024
	ds_read_b128 v[154:157], v149 offset:2048
	ds_read_b128 v[158:161], v149 offset:3072
	v_add_u32_e32 v149, s9, v145
	ds_read_b128 v[162:165], v149
	ds_read_b128 v[166:169], v149 offset:1024
	ds_read_b128 v[170:173], v149 offset:2048
	ds_read_b128 v[174:177], v149 offset:3072
	s_add_u32 s50, s50, 0x40000
	s_addc_u32 s51, s51, 0
	s_mov_b32 m0, s59
	v_lshl_add_u64 v[222:223], s[50:51], 0, v[128:129]
	ds_read_b128 v[178:181], v148 offset:32768
	ds_read_b128 v[182:185], v148 offset:33792
	ds_read_b128 v[186:189], v148 offset:34816
	ds_read_b128 v[196:199], v148 offset:35840
	ds_read_b128 v[200:203], v148 offset:36864
	ds_read_b128 v[204:207], v148 offset:37888
	ds_read_b128 v[208:211], v148 offset:38912
	ds_read_b128 v[212:215], v148 offset:39936
	global_load_lds_dwordx4 v[222:223], off nt
	v_lshl_add_u64 v[222:223], s[50:51], 0, v[130:131]
	s_mov_b32 m0, s60
	s_nop 0
	global_load_lds_dwordx4 v[222:223], off nt
	s_waitcnt vmcnt(8)
	s_waitcnt lgkmcnt(0)
	s_barrier
	s_setprio 1
	s_waitcnt lgkmcnt(0)
	v_mfma_f32_16x16x32_bf16 v[124:127], v[140:143], v[178:181], v[124:127]
	v_mfma_f32_16x16x32_bf16 v[120:123], v[154:157], v[178:181], v[120:123]
	v_mfma_f32_16x16x32_bf16 v[108:111], v[140:143], v[186:189], v[108:111]
	v_mfma_f32_16x16x32_bf16 v[104:107], v[154:157], v[186:189], v[104:107]
	v_mfma_f32_16x16x32_bf16 v[92:95], v[140:143], v[200:203], v[92:95]
	v_mfma_f32_16x16x32_bf16 v[88:91], v[154:157], v[200:203], v[88:91]
	v_mfma_f32_16x16x32_bf16 v[76:79], v[140:143], v[208:211], v[76:79]
	v_mfma_f32_16x16x32_bf16 v[72:75], v[154:157], v[208:211], v[72:75]
	v_mfma_f32_16x16x32_bf16 v[124:127], v[150:153], v[182:185], v[124:127]
	v_mfma_f32_16x16x32_bf16 v[120:123], v[158:161], v[182:185], v[120:123]
	v_mfma_f32_16x16x32_bf16 v[108:111], v[150:153], v[196:199], v[108:111]
	v_mfma_f32_16x16x32_bf16 v[104:107], v[158:161], v[196:199], v[104:107]
	v_mfma_f32_16x16x32_bf16 v[92:95], v[150:153], v[204:207], v[92:95]
	v_mfma_f32_16x16x32_bf16 v[88:91], v[158:161], v[204:207], v[88:91]
	v_mfma_f32_16x16x32_bf16 v[76:79], v[150:153], v[212:215], v[76:79]
	v_mfma_f32_16x16x32_bf16 v[72:75], v[158:161], v[212:215], v[72:75]
	s_setprio 0
	s_setprio 1
	v_mfma_f32_16x16x32_bf16 v[116:119], v[162:165], v[178:181], v[116:119]
	v_mfma_f32_16x16x32_bf16 v[112:115], v[170:173], v[178:181], v[112:115]
	v_mfma_f32_16x16x32_bf16 v[100:103], v[162:165], v[186:189], v[100:103]
	v_mfma_f32_16x16x32_bf16 v[96:99], v[170:173], v[186:189], v[96:99]
	v_mfma_f32_16x16x32_bf16 v[84:87], v[162:165], v[200:203], v[84:87]
	v_mfma_f32_16x16x32_bf16 v[80:83], v[170:173], v[200:203], v[80:83]
	v_mfma_f32_16x16x32_bf16 v[68:71], v[162:165], v[208:211], v[68:71]
	v_mfma_f32_16x16x32_bf16 v[64:67], v[170:173], v[208:211], v[64:67]
	v_mfma_f32_16x16x32_bf16 v[116:119], v[166:169], v[182:185], v[116:119]
	v_mfma_f32_16x16x32_bf16 v[112:115], v[174:177], v[182:185], v[112:115]
	v_mfma_f32_16x16x32_bf16 v[100:103], v[166:169], v[196:199], v[100:103]
	v_mfma_f32_16x16x32_bf16 v[96:99], v[174:177], v[196:199], v[96:99]
	v_mfma_f32_16x16x32_bf16 v[84:87], v[166:169], v[204:207], v[84:87]
	v_mfma_f32_16x16x32_bf16 v[80:83], v[174:177], v[204:207], v[80:83]
	v_mfma_f32_16x16x32_bf16 v[68:71], v[166:169], v[212:215], v[68:71]
	v_mfma_f32_16x16x32_bf16 v[64:67], v[174:177], v[212:215], v[64:67]
	s_setprio 0
	s_barrier
	s_add_i32 s8, s8, s56
	v_lshl_add_u64 v[190:191], v[190:191], 0, s[24:25]
	s_mov_b32 m0, s8
	ds_read_b128 v[178:181], v148 offset:49152
	ds_read_b128 v[182:185], v148 offset:50176
	ds_read_b128 v[186:189], v148 offset:51200
	ds_read_b128 v[196:199], v148 offset:52224
	ds_read_b128 v[200:203], v148 offset:53248
	ds_read_b128 v[204:207], v148 offset:54272
	ds_read_b128 v[208:211], v148 offset:55296
	ds_read_b128 v[212:215], v148 offset:56320
	global_load_lds_dwordx4 v[190:191], off nt
	s_add_i32 m0, s8, 0x2000
	s_add_u32 s48, s48, 0x40080
	v_lshl_add_u64 v[190:191], v[216:217], 0, s[24:25]
	s_addc_u32 s49, s49, 0
	s_add_i32 s8, s9, s56
	global_load_lds_dwordx4 v[190:191], off nt
	v_lshl_add_u64 v[190:191], s[48:49], 0, v[128:129]
	s_mov_b32 m0, s8
	s_nop 0
	global_load_lds_dwordx4 v[190:191], off nt
	v_lshl_add_u64 v[190:191], s[48:49], 0, v[130:131]
	s_add_i32 m0, s8, 0x2000
	s_nop 0
	global_load_lds_dwordx4 v[190:191], off nt
	v_lshl_add_u64 v[190:191], v[218:219], 0, s[24:25]
	s_mov_b32 m0, s61
	s_nop 0
	global_load_lds_dwordx4 v[190:191], off nt
	v_lshl_add_u64 v[190:191], v[220:221], 0, s[24:25]
	s_mov_b32 m0, s62
	s_nop 0
	global_load_lds_dwordx4 v[190:191], off nt
	s_waitcnt vmcnt(8)
	s_waitcnt lgkmcnt(0)
	s_barrier
	s_setprio 1
	s_waitcnt lgkmcnt(0)
	v_mfma_f32_16x16x32_bf16 v[60:63], v[140:143], v[178:181], v[60:63]
	v_mfma_f32_16x16x32_bf16 v[56:59], v[154:157], v[178:181], v[56:59]
	v_mfma_f32_16x16x32_bf16 v[44:47], v[140:143], v[186:189], v[44:47]
	v_mfma_f32_16x16x32_bf16 v[40:43], v[154:157], v[186:189], v[40:43]
	v_mfma_f32_16x16x32_bf16 v[28:31], v[140:143], v[200:203], v[28:31]
	v_mfma_f32_16x16x32_bf16 v[24:27], v[154:157], v[200:203], v[24:27]
	v_mfma_f32_16x16x32_bf16 v[12:15], v[140:143], v[208:211], v[12:15]
	v_mfma_f32_16x16x32_bf16 v[8:11], v[154:157], v[208:211], v[8:11]
	v_mfma_f32_16x16x32_bf16 v[60:63], v[150:153], v[182:185], v[60:63]
	v_mfma_f32_16x16x32_bf16 v[56:59], v[158:161], v[182:185], v[56:59]
	v_mfma_f32_16x16x32_bf16 v[44:47], v[150:153], v[196:199], v[44:47]
	v_mfma_f32_16x16x32_bf16 v[40:43], v[158:161], v[196:199], v[40:43]
	v_mfma_f32_16x16x32_bf16 v[28:31], v[150:153], v[204:207], v[28:31]
	v_mfma_f32_16x16x32_bf16 v[24:27], v[158:161], v[204:207], v[24:27]
	v_mfma_f32_16x16x32_bf16 v[12:15], v[150:153], v[212:215], v[12:15]
	v_mfma_f32_16x16x32_bf16 v[8:11], v[158:161], v[212:215], v[8:11]
	s_setprio 0
	s_setprio 1
	v_mfma_f32_16x16x32_bf16 v[52:55], v[162:165], v[178:181], v[52:55]
	v_mfma_f32_16x16x32_bf16 v[48:51], v[170:173], v[178:181], v[48:51]
	v_mfma_f32_16x16x32_bf16 v[36:39], v[162:165], v[186:189], v[36:39]
	v_mfma_f32_16x16x32_bf16 v[32:35], v[170:173], v[186:189], v[32:35]
	v_mfma_f32_16x16x32_bf16 v[20:23], v[162:165], v[200:203], v[20:23]
	v_mfma_f32_16x16x32_bf16 v[16:19], v[170:173], v[200:203], v[16:19]
	v_mfma_f32_16x16x32_bf16 v[4:7], v[162:165], v[208:211], v[4:7]
	v_mfma_f32_16x16x32_bf16 v[0:3], v[170:173], v[208:211], v[0:3]
	v_mfma_f32_16x16x32_bf16 v[52:55], v[166:169], v[182:185], v[52:55]
	v_mfma_f32_16x16x32_bf16 v[48:51], v[174:177], v[182:185], v[48:51]
	v_mfma_f32_16x16x32_bf16 v[36:39], v[166:169], v[196:199], v[36:39]
	v_mfma_f32_16x16x32_bf16 v[32:35], v[174:177], v[196:199], v[32:35]
	v_mfma_f32_16x16x32_bf16 v[20:23], v[166:169], v[204:207], v[20:23]
	v_mfma_f32_16x16x32_bf16 v[16:19], v[174:177], v[204:207], v[16:19]
	v_mfma_f32_16x16x32_bf16 v[4:7], v[166:169], v[212:215], v[4:7]
	v_mfma_f32_16x16x32_bf16 v[0:3], v[174:177], v[212:215], v[0:3]
	s_setprio 0
	s_barrier
	s_add_i32 s72, s72, 2
	s_add_u32 s46, s46, 0x100
	s_addc_u32 s47, s47, 0
	s_add_u32 s70, s70, 0x100
	s_addc_u32 s71, s71, 0
	s_cmp_gt_u32 s72, 13
	s_cbranch_scc0 .LBB0_382
	s_and_b64 vcc, exec, s[26:27]
	s_cbranch_vccz .LBB0_385
	s_barrier
